# removed per-cluster s_setprio flips in the three GEMM K loops
# speedup vs baseline: 1.0619x; 1.0049x over previous
; #define PG8_STAGE(bufoff, gbase, voff) do { _Pragma("unroll") for (int _i = 0; _i < 2; ++_i) \
;         __builtin_amdgcn_global_load_lds((const unsigned*)((const char*)(gbase) + (voff)[_i]), (LAS unsigned*)(lds + (bufoff) + ldsw + _i * 8192), 16, 0, 0); } while (0)
; #define PG8_LDA(dst, b, h) do { _Pragma("unroll") for (int m = 0; m < 4; ++m) _Pragma("unroll") for (int k = 0; k < 2; ++k) dst[m][k] = *(const LAS bf16x8*)(lds + PG8_SA(b, h) + aoff + m * 2048 + k * 1024); } while (0)
; #define PG8_LDB(dst, b, h) do { _Pragma("unroll") for (int n = 0; n < 2; ++n) _Pragma("unroll") for (int k = 0; k < 2; ++k) dst[n][k] = *(const LAS bf16x8*)(lds + PG8_SB(b, h) + boff + n * 2048 + k * 1024); } while (0)
; #define PG8_WAIT_V(n) asm volatile("s_waitcnt vmcnt(" #n ")" ::: "memory")
; #define PG8_BAR __builtin_amdgcn_s_barrier()
; template <class Epi>
; __device__ __forceinline__ void gemm_phase(LAS unsigned char* lds, const Gemm g, const StaticOrder& S, const Epi& E, const float* SS) {
;     ...
;         for (int t = 0; t < nt; t += 2) {
;             const bool last = (t == nt - 2);
;             const char* a1 = cA + (size_t)(t + 1) * kstep;
;             const char* a2 = last ? nA : cA + (size_t)(t + 2) * kstep; const char* b2 = last ? nB : cB + (size_t)(t + 2) * kstep;
;             const char* a3 = a2 + kstep; const char* b3 = b2 + kstep;
;             PG8_LDB(B0, 0, 0); PG8_LDB(B1, 0, 1); PG8_SCHED; PG8_LDA(At, 0, 0); PG8_STAGE(PG8_SA(1, 1), a1 + hstep, voffA);
;             PG8_WAIT_V(8); PG8_WAIT_L(0); PG8_BAR; PG8_MMA(0, 0, At, B0); PG8_MMA(0, 1, At, B1); PG8_BAR; PG8_SCHED;
;             PG8_LDA(At, 0, 1); PG8_STAGE(PG8_SB(0, 0), b2, voffB); PG8_STAGE(PG8_SB(0, 1), b2 + hstep, voffB); PG8_STAGE(PG8_SA(0, 0), a2, voffA);
;             PG8_WAIT_V(8); PG8_WAIT_L(0); PG8_BAR; PG8_MMA(1, 0, At, B0); PG8_MMA(1, 1, At, B1); PG8_BAR; PG8_SCHED;
;             PG8_LDB(B0, 1, 0); PG8_LDB(B1, 1, 1); PG8_SCHED; PG8_LDA(At, 1, 0); PG8_STAGE(PG8_SA(0, 1), a2 + hstep, voffA);
;             PG8_WAIT_V(8); PG8_WAIT_L(0); PG8_BAR; PG8_MMA(0, 0, At, B0); PG8_MMA(0, 1, At, B1); PG8_BAR; PG8_SCHED;
;             PG8_LDA(At, 1, 1); PG8_STAGE(PG8_SB(1, 0), b3, voffB); PG8_STAGE(PG8_SB(1, 1), b3 + hstep, voffB); PG8_STAGE(PG8_SA(1, 0), a3, voffA);
;             PG8_WAIT_V(8); PG8_WAIT_L(0); PG8_BAR; PG8_MMA(1, 0, At, B0); PG8_MMA(1, 1, At, B1); PG8_BAR; PG8_SCHED;
;         }
.LBB0_380:
	s_add_u32 s36, s18, s34
	s_addc_u32 s37, s19, s35
	s_add_u32 s36, s36, 0x100
	s_addc_u32 s37, s37, 0
	s_add_u32 s52, s4, s34
	s_addc_u32 s53, s5, s35
	s_add_i32 s54, 0, 0x10000
	s_cmpk_eq_i32 s34, 0x700
	s_cselect_b32 s39, s27, s37
	s_cselect_b32 s38, s49, s36
	s_cselect_b32 s37, s25, s53
	s_cselect_b32 s36, s50, s52
	s_add_i32 s55, 0, 0x14000
	v_add_u32_e32 v168, s54, v145
	v_add_u32_e32 v184, s55, v145
	ds_read_b128 v[156:159], v168
	ds_read_b128 v[160:163], v168 offset:1024
	ds_read_b128 v[164:167], v168 offset:2048
	ds_read_b128 v[168:171], v168 offset:3072
	ds_read_b128 v[172:175], v184
	ds_read_b128 v[176:179], v184 offset:1024
	ds_read_b128 v[180:183], v184 offset:2048
	ds_read_b128 v[184:187], v184 offset:3072
	v_lshl_add_u64 v[196:197], v[142:143], 0, s[34:35]
	s_add_i32 m0, s15, 0xc000
	ds_read_b128 v[188:191], v155
	ds_read_b128 v[192:195], v155 offset:1024
	ds_read_b128 v[200:203], v155 offset:2048
	ds_read_b128 v[204:207], v155 offset:3072
	ds_read_b128 v[216:219], v155 offset:4096
	ds_read_b128 v[220:223], v155 offset:5120
	ds_read_b128 v[224:227], v155 offset:6144
	ds_read_b128 v[228:231], v155 offset:7168
	global_load_lds_dwordx4 v[196:197], off
	v_lshl_add_u64 v[196:197], v[140:141], 0, s[34:35]
	s_add_i32 m0, s15, 0xe000
	s_nop 0
	global_load_lds_dwordx4 v[196:197], off
	s_waitcnt vmcnt(8)
	s_waitcnt lgkmcnt(0)
	s_barrier
	s_waitcnt lgkmcnt(0)
	v_mfma_f32_16x16x32_bf16 v[94:97], v[156:159], v[188:191], v[94:97]
	v_mfma_f32_16x16x32_bf16 v[90:93], v[164:167], v[188:191], v[90:93]
	v_mfma_f32_16x16x32_bf16 v[86:89], v[156:159], v[200:203], v[86:89]
	v_mfma_f32_16x16x32_bf16 v[82:85], v[164:167], v[200:203], v[82:85]
	v_mfma_f32_16x16x32_bf16 v[78:81], v[156:159], v[216:219], v[78:81]
	v_mfma_f32_16x16x32_bf16 v[74:77], v[164:167], v[216:219], v[74:77]
	v_mfma_f32_16x16x32_bf16 v[70:73], v[156:159], v[224:227], v[70:73]
	v_mfma_f32_16x16x32_bf16 v[66:69], v[164:167], v[224:227], v[66:69]
	v_mfma_f32_16x16x32_bf16 v[94:97], v[160:163], v[192:195], v[94:97]
	v_mfma_f32_16x16x32_bf16 v[90:93], v[168:171], v[192:195], v[90:93]
	v_mfma_f32_16x16x32_bf16 v[86:89], v[160:163], v[204:207], v[86:89]
	v_mfma_f32_16x16x32_bf16 v[82:85], v[168:171], v[204:207], v[82:85]
	v_mfma_f32_16x16x32_bf16 v[78:81], v[160:163], v[220:223], v[78:81]
	v_mfma_f32_16x16x32_bf16 v[74:77], v[168:171], v[220:223], v[74:77]
	v_mfma_f32_16x16x32_bf16 v[70:73], v[160:163], v[228:231], v[70:73]
	v_mfma_f32_16x16x32_bf16 v[66:69], v[168:171], v[228:231], v[66:69]
	v_mfma_f32_16x16x32_bf16 v[62:65], v[172:175], v[188:191], v[62:65]
	v_mfma_f32_16x16x32_bf16 v[58:61], v[180:183], v[188:191], v[58:61]
	v_mfma_f32_16x16x32_bf16 v[54:57], v[172:175], v[200:203], v[54:57]
	v_mfma_f32_16x16x32_bf16 v[50:53], v[180:183], v[200:203], v[50:53]
	v_mfma_f32_16x16x32_bf16 v[46:49], v[172:175], v[216:219], v[46:49]
	v_mfma_f32_16x16x32_bf16 v[42:45], v[180:183], v[216:219], v[42:45]
	v_mfma_f32_16x16x32_bf16 v[38:41], v[172:175], v[224:227], v[38:41]
	v_mfma_f32_16x16x32_bf16 v[34:37], v[180:183], v[224:227], v[34:37]
	v_mfma_f32_16x16x32_bf16 v[62:65], v[176:179], v[192:195], v[62:65]
	v_mfma_f32_16x16x32_bf16 v[58:61], v[184:187], v[192:195], v[58:61]
	v_mfma_f32_16x16x32_bf16 v[54:57], v[176:179], v[204:207], v[54:57]
	v_mfma_f32_16x16x32_bf16 v[50:53], v[184:187], v[204:207], v[50:53]
	v_mfma_f32_16x16x32_bf16 v[46:49], v[176:179], v[220:223], v[46:49]
	v_mfma_f32_16x16x32_bf16 v[42:45], v[184:187], v[220:223], v[42:45]
	v_mfma_f32_16x16x32_bf16 v[38:41], v[176:179], v[228:231], v[38:41]
	v_mfma_f32_16x16x32_bf16 v[34:37], v[184:187], v[228:231], v[34:37]
	s_barrier
	s_add_i32 s52, s54, s41
	v_lshl_add_u64 v[196:197], s[36:37], 0, v[0:1]
	s_mov_b32 m0, s52
	ds_read_b128 v[188:191], v155 offset:16384
	ds_read_b128 v[192:195], v155 offset:17408
	ds_read_b128 v[200:203], v155 offset:18432
	ds_read_b128 v[204:207], v155 offset:19456
	ds_read_b128 v[216:219], v155 offset:20480
	ds_read_b128 v[220:223], v155 offset:21504
	ds_read_b128 v[224:227], v155 offset:22528
	ds_read_b128 v[228:231], v155 offset:23552
	global_load_lds_dwordx4 v[196:197], off
	s_add_i32 m0, s52, 0x2000
	s_add_u32 s52, s36, 0x40000
	v_lshl_add_u64 v[232:233], s[36:37], 0, v[134:135]
	s_addc_u32 s53, s37, 0
	s_add_i32 s54, s55, s41
	global_load_lds_dwordx4 v[232:233], off
	v_lshl_add_u64 v[234:235], s[52:53], 0, v[0:1]
	s_mov_b32 m0, s54
	v_lshl_add_u64 v[236:237], s[38:39], 0, v[132:133]
	global_load_lds_dwordx4 v[234:235], off
	v_lshl_add_u64 v[234:235], s[52:53], 0, v[134:135]
	s_add_i32 m0, s54, 0x2000
	s_nop 0
	global_load_lds_dwordx4 v[234:235], off
	v_lshl_add_u64 v[234:235], s[38:39], 0, v[130:131]
	s_mov_b32 m0, s15
	s_nop 0
	global_load_lds_dwordx4 v[234:235], off
	s_mov_b32 m0, s17
	s_nop 0
	global_load_lds_dwordx4 v[236:237], off
	s_waitcnt vmcnt(8)
	s_waitcnt lgkmcnt(0)
	s_barrier
; #define PG8_STAGE(bufoff, gbase, voff) do { _Pragma("unroll") for (int _i = 0; _i < 2; ++_i) \
;         __builtin_amdgcn_global_load_lds((const unsigned*)((const char*)(gbase) + (voff)[_i]), (LAS unsigned*)(lds + (bufoff) + ldsw + _i * 8192), 16, 0, 0); } while (0)
; #define PG8_LDA(dst, b, h) do { _Pragma("unroll") for (int m = 0; m < 4; ++m) _Pragma("unroll") for (int k = 0; k < 2; ++k) dst[m][k] = *(const LAS bf16x8*)(lds + PG8_SA(b, h) + aoff + m * 2048 + k * 1024); } while (0)
; #define PG8_LDB(dst, b, h) do { _Pragma("unroll") for (int n = 0; n < 2; ++n) _Pragma("unroll") for (int k = 0; k < 2; ++k) dst[n][k] = *(const LAS bf16x8*)(lds + PG8_SB(b, h) + boff + n * 2048 + k * 1024); } while (0)
; #define PG8_WAIT_V(n) asm volatile("s_waitcnt vmcnt(" #n ")" ::: "memory")
; #define PG8_BAR __builtin_amdgcn_s_barrier()
; template <class Epi>
; __device__ __forceinline__ void gemm_phase(LAS unsigned char* lds, const Gemm g, const StaticOrder& S, const Epi& E, const float* SS) {
;     ...
;         for (int t = 0; t < nt; t += 2) {
;             const bool last = (t == nt - 2);
;             const char* a1 = cA + (size_t)(t + 1) * kstep;
;             const char* a2 = last ? nA : cA + (size_t)(t + 2) * kstep; const char* b2 = last ? nB : cB + (size_t)(t + 2) * kstep;
;             const char* a3 = a2 + kstep; const char* b3 = b2 + kstep;
;             PG8_LDB(B0, 0, 0); PG8_LDB(B1, 0, 1); PG8_SCHED; PG8_LDA(At, 0, 0); PG8_STAGE(PG8_SA(1, 1), a1 + hstep, voffA);
;             PG8_WAIT_V(8); PG8_WAIT_L(0); PG8_BAR; PG8_MMA(0, 0, At, B0); PG8_MMA(0, 1, At, B1); PG8_BAR; PG8_SCHED;
;             PG8_LDA(At, 0, 1); PG8_STAGE(PG8_SB(0, 0), b2, voffB); PG8_STAGE(PG8_SB(0, 1), b2 + hstep, voffB); PG8_STAGE(PG8_SA(0, 0), a2, voffA);
;             PG8_WAIT_V(8); PG8_WAIT_L(0); PG8_BAR; PG8_MMA(1, 0, At, B0); PG8_MMA(1, 1, At, B1); PG8_BAR; PG8_SCHED;
;             PG8_LDB(B0, 1, 0); PG8_LDB(B1, 1, 1); PG8_SCHED; PG8_LDA(At, 1, 0); PG8_STAGE(PG8_SA(0, 1), a2 + hstep, voffA);
;             PG8_WAIT_V(8); PG8_WAIT_L(0); PG8_BAR; PG8_MMA(0, 0, At, B0); PG8_MMA(0, 1, At, B1); PG8_BAR; PG8_SCHED;
;             PG8_LDA(At, 1, 1); PG8_STAGE(PG8_SB(1, 0), b3, voffB); PG8_STAGE(PG8_SB(1, 1), b3 + hstep, voffB); PG8_STAGE(PG8_SA(1, 0), a3, voffA);
;             PG8_WAIT_V(8); PG8_WAIT_L(0); PG8_BAR; PG8_MMA(1, 0, At, B0); PG8_MMA(1, 1, At, B1); PG8_BAR; PG8_SCHED;
;         }
	s_waitcnt lgkmcnt(0)
	v_mfma_f32_16x16x32_bf16 v[30:33], v[156:159], v[188:191], v[30:33]
	v_mfma_f32_16x16x32_bf16 v[26:29], v[164:167], v[188:191], v[26:29]
	v_mfma_f32_16x16x32_bf16 v[22:25], v[156:159], v[200:203], v[22:25]
	v_mfma_f32_16x16x32_bf16 v[18:21], v[164:167], v[200:203], v[18:21]
	v_mfma_f32_16x16x32_bf16 v[14:17], v[156:159], v[216:219], v[14:17]
	v_mfma_f32_16x16x32_bf16 v[10:13], v[164:167], v[216:219], v[10:13]
	v_mfma_f32_16x16x32_bf16 v[6:9], v[156:159], v[224:227], v[6:9]
	v_mfma_f32_16x16x32_bf16 v[2:5], v[164:167], v[224:227], v[2:5]
	v_mfma_f32_16x16x32_bf16 v[30:33], v[160:163], v[192:195], v[30:33]
	v_mfma_f32_16x16x32_bf16 v[26:29], v[168:171], v[192:195], v[26:29]
	v_mfma_f32_16x16x32_bf16 v[22:25], v[160:163], v[204:207], v[22:25]
	v_mfma_f32_16x16x32_bf16 v[18:21], v[168:171], v[204:207], v[18:21]
	v_mfma_f32_16x16x32_bf16 v[14:17], v[160:163], v[220:223], v[14:17]
	v_mfma_f32_16x16x32_bf16 v[10:13], v[168:171], v[220:223], v[10:13]
	v_mfma_f32_16x16x32_bf16 v[6:9], v[160:163], v[228:231], v[6:9]
	v_mfma_f32_16x16x32_bf16 v[2:5], v[168:171], v[228:231], v[2:5]
	v_mfma_f32_16x16x32_bf16 v[98:101], v[172:175], v[188:191], v[98:101]
	v_mfma_f32_16x16x32_bf16 v[102:105], v[180:183], v[188:191], v[102:105]
	v_mfma_f32_16x16x32_bf16 v[106:109], v[172:175], v[200:203], v[106:109]
	v_mfma_f32_16x16x32_bf16 v[110:113], v[180:183], v[200:203], v[110:113]
	v_mfma_f32_16x16x32_bf16 v[114:117], v[172:175], v[216:219], v[114:117]
	v_mfma_f32_16x16x32_bf16 v[118:121], v[180:183], v[216:219], v[118:121]
	v_mfma_f32_16x16x32_bf16 v[122:125], v[172:175], v[224:227], v[122:125]
	v_mfma_f32_16x16x32_bf16 v[126:129], v[180:183], v[224:227], v[126:129]
	v_mfma_f32_16x16x32_bf16 v[98:101], v[176:179], v[192:195], v[98:101]
	v_mfma_f32_16x16x32_bf16 v[102:105], v[184:187], v[192:195], v[102:105]
	v_mfma_f32_16x16x32_bf16 v[106:109], v[176:179], v[204:207], v[106:109]
	v_mfma_f32_16x16x32_bf16 v[110:113], v[184:187], v[204:207], v[110:113]
	v_mfma_f32_16x16x32_bf16 v[114:117], v[176:179], v[220:223], v[114:117]
	v_mfma_f32_16x16x32_bf16 v[118:121], v[184:187], v[220:223], v[118:121]
	v_mfma_f32_16x16x32_bf16 v[122:125], v[176:179], v[228:231], v[122:125]
	v_mfma_f32_16x16x32_bf16 v[126:129], v[184:187], v[228:231], v[126:129]
	s_barrier
	s_add_i32 s52, 0, 0x18000
	s_add_i32 s53, 0, 0x1c000
	v_add_u32_e32 v168, s52, v145
	v_add_u32_e32 v184, s53, v145
	ds_read_b128 v[156:159], v168
	ds_read_b128 v[160:163], v168 offset:1024
	ds_read_b128 v[164:167], v168 offset:2048
	ds_read_b128 v[168:171], v168 offset:3072
	ds_read_b128 v[172:175], v184
	ds_read_b128 v[176:179], v184 offset:1024
	ds_read_b128 v[180:183], v184 offset:2048
	ds_read_b128 v[184:187], v184 offset:3072
	s_add_u32 s38, s38, 0x40000
	s_addc_u32 s39, s39, 0
	s_mov_b32 m0, s42
	v_lshl_add_u64 v[238:239], s[38:39], 0, v[130:131]
	ds_read_b128 v[188:191], v155 offset:32768
	ds_read_b128 v[192:195], v155 offset:33792
	ds_read_b128 v[200:203], v155 offset:34816
	ds_read_b128 v[204:207], v155 offset:35840
	ds_read_b128 v[216:219], v155 offset:36864
	ds_read_b128 v[220:223], v155 offset:37888
	ds_read_b128 v[224:227], v155 offset:38912
	ds_read_b128 v[228:231], v155 offset:39936
	global_load_lds_dwordx4 v[238:239], off
	v_lshl_add_u64 v[238:239], s[38:39], 0, v[132:133]
	s_mov_b32 m0, s43
	s_nop 0
	global_load_lds_dwordx4 v[238:239], off
	s_waitcnt vmcnt(8)
	s_waitcnt lgkmcnt(0)
	s_barrier
	s_waitcnt lgkmcnt(0)
	v_mfma_f32_16x16x32_bf16 v[94:97], v[156:159], v[188:191], v[94:97]
	v_mfma_f32_16x16x32_bf16 v[90:93], v[164:167], v[188:191], v[90:93]
	v_mfma_f32_16x16x32_bf16 v[86:89], v[156:159], v[200:203], v[86:89]
	v_mfma_f32_16x16x32_bf16 v[82:85], v[164:167], v[200:203], v[82:85]
	v_mfma_f32_16x16x32_bf16 v[78:81], v[156:159], v[216:219], v[78:81]
	v_mfma_f32_16x16x32_bf16 v[74:77], v[164:167], v[216:219], v[74:77]
	v_mfma_f32_16x16x32_bf16 v[70:73], v[156:159], v[224:227], v[70:73]
	v_mfma_f32_16x16x32_bf16 v[66:69], v[164:167], v[224:227], v[66:69]
	v_mfma_f32_16x16x32_bf16 v[94:97], v[160:163], v[192:195], v[94:97]
	v_mfma_f32_16x16x32_bf16 v[90:93], v[168:171], v[192:195], v[90:93]
	v_mfma_f32_16x16x32_bf16 v[86:89], v[160:163], v[204:207], v[86:89]
	v_mfma_f32_16x16x32_bf16 v[82:85], v[168:171], v[204:207], v[82:85]
	v_mfma_f32_16x16x32_bf16 v[78:81], v[160:163], v[220:223], v[78:81]
	v_mfma_f32_16x16x32_bf16 v[74:77], v[168:171], v[220:223], v[74:77]
	v_mfma_f32_16x16x32_bf16 v[70:73], v[160:163], v[228:231], v[70:73]
	v_mfma_f32_16x16x32_bf16 v[66:69], v[168:171], v[228:231], v[66:69]
	v_mfma_f32_16x16x32_bf16 v[62:65], v[172:175], v[188:191], v[62:65]
	v_mfma_f32_16x16x32_bf16 v[58:61], v[180:183], v[188:191], v[58:61]
	v_mfma_f32_16x16x32_bf16 v[54:57], v[172:175], v[200:203], v[54:57]
	v_mfma_f32_16x16x32_bf16 v[50:53], v[180:183], v[200:203], v[50:53]
	v_mfma_f32_16x16x32_bf16 v[46:49], v[172:175], v[216:219], v[46:49]
	v_mfma_f32_16x16x32_bf16 v[42:45], v[180:183], v[216:219], v[42:45]
	v_mfma_f32_16x16x32_bf16 v[38:41], v[172:175], v[224:227], v[38:41]
	v_mfma_f32_16x16x32_bf16 v[34:37], v[180:183], v[224:227], v[34:37]
	v_mfma_f32_16x16x32_bf16 v[62:65], v[176:179], v[192:195], v[62:65]
	v_mfma_f32_16x16x32_bf16 v[58:61], v[184:187], v[192:195], v[58:61]
	v_mfma_f32_16x16x32_bf16 v[54:57], v[176:179], v[204:207], v[54:57]
	v_mfma_f32_16x16x32_bf16 v[50:53], v[184:187], v[204:207], v[50:53]
	v_mfma_f32_16x16x32_bf16 v[46:49], v[176:179], v[220:223], v[46:49]
	v_mfma_f32_16x16x32_bf16 v[42:45], v[184:187], v[220:223], v[42:45]
	v_mfma_f32_16x16x32_bf16 v[38:41], v[176:179], v[228:231], v[38:41]
	v_mfma_f32_16x16x32_bf16 v[34:37], v[184:187], v[228:231], v[34:37]
	s_barrier
; #define PG8_STAGE(bufoff, gbase, voff) do { _Pragma("unroll") for (int _i = 0; _i < 2; ++_i) \
;         __builtin_amdgcn_global_load_lds((const unsigned*)((const char*)(gbase) + (voff)[_i]), (LAS unsigned*)(lds + (bufoff) + ldsw + _i * 8192), 16, 0, 0); } while (0)
; #define PG8_LDA(dst, b, h) do { _Pragma("unroll") for (int m = 0; m < 4; ++m) _Pragma("unroll") for (int k = 0; k < 2; ++k) dst[m][k] = *(const LAS bf16x8*)(lds + PG8_SA(b, h) + aoff + m * 2048 + k * 1024); } while (0)
; #define PG8_LDB(dst, b, h) do { _Pragma("unroll") for (int n = 0; n < 2; ++n) _Pragma("unroll") for (int k = 0; k < 2; ++k) dst[n][k] = *(const LAS bf16x8*)(lds + PG8_SB(b, h) + boff + n * 2048 + k * 1024); } while (0)
; #define PG8_WAIT_V(n) asm volatile("s_waitcnt vmcnt(" #n ")" ::: "memory")
; #define PG8_BAR __builtin_amdgcn_s_barrier()
; template <class Epi>
; __device__ __forceinline__ void gemm_phase(LAS unsigned char* lds, const Gemm g, const StaticOrder& S, const Epi& E, const float* SS) {
;     ...
;         for (int t = 0; t < nt; t += 2) {
;             const bool last = (t == nt - 2);
;             const char* a1 = cA + (size_t)(t + 1) * kstep;
;             const char* a2 = last ? nA : cA + (size_t)(t + 2) * kstep; const char* b2 = last ? nB : cB + (size_t)(t + 2) * kstep;
;             const char* a3 = a2 + kstep; const char* b3 = b2 + kstep;
;             PG8_LDB(B0, 0, 0); PG8_LDB(B1, 0, 1); PG8_SCHED; PG8_LDA(At, 0, 0); PG8_STAGE(PG8_SA(1, 1), a1 + hstep, voffA);
;             PG8_WAIT_V(8); PG8_WAIT_L(0); PG8_BAR; PG8_MMA(0, 0, At, B0); PG8_MMA(0, 1, At, B1); PG8_BAR; PG8_SCHED;
;             PG8_LDA(At, 0, 1); PG8_STAGE(PG8_SB(0, 0), b2, voffB); PG8_STAGE(PG8_SB(0, 1), b2 + hstep, voffB); PG8_STAGE(PG8_SA(0, 0), a2, voffA);
;             PG8_WAIT_V(8); PG8_WAIT_L(0); PG8_BAR; PG8_MMA(1, 0, At, B0); PG8_MMA(1, 1, At, B1); PG8_BAR; PG8_SCHED;
;             PG8_LDB(B0, 1, 0); PG8_LDB(B1, 1, 1); PG8_SCHED; PG8_LDA(At, 1, 0); PG8_STAGE(PG8_SA(0, 1), a2 + hstep, voffA);
;             PG8_WAIT_V(8); PG8_WAIT_L(0); PG8_BAR; PG8_MMA(0, 0, At, B0); PG8_MMA(0, 1, At, B1); PG8_BAR; PG8_SCHED;
;             PG8_LDA(At, 1, 1); PG8_STAGE(PG8_SB(1, 0), b3, voffB); PG8_STAGE(PG8_SB(1, 1), b3 + hstep, voffB); PG8_STAGE(PG8_SA(1, 0), a3, voffA);
;             PG8_WAIT_V(8); PG8_WAIT_L(0); PG8_BAR; PG8_MMA(1, 0, At, B0); PG8_MMA(1, 1, At, B1); PG8_BAR; PG8_SCHED;
;         }
	s_add_i32 s38, s52, s41
	v_lshl_add_u64 v[196:197], v[196:197], 0, s[64:65]
	s_mov_b32 m0, s38
	ds_read_b128 v[188:191], v155 offset:49152
	ds_read_b128 v[192:195], v155 offset:50176
	ds_read_b128 v[200:203], v155 offset:51200
	ds_read_b128 v[204:207], v155 offset:52224
	ds_read_b128 v[216:219], v155 offset:53248
	ds_read_b128 v[220:223], v155 offset:54272
	ds_read_b128 v[224:227], v155 offset:55296
	ds_read_b128 v[228:231], v155 offset:56320
	global_load_lds_dwordx4 v[196:197], off
	s_add_i32 m0, s38, 0x2000
	s_add_u32 s36, s36, 0x40080
	v_lshl_add_u64 v[196:197], v[232:233], 0, s[64:65]
	s_addc_u32 s37, s37, 0
	s_add_i32 s38, s53, s41
	global_load_lds_dwordx4 v[196:197], off
	v_lshl_add_u64 v[196:197], s[36:37], 0, v[0:1]
	s_mov_b32 m0, s38
	s_nop 0
	global_load_lds_dwordx4 v[196:197], off
	v_lshl_add_u64 v[196:197], s[36:37], 0, v[134:135]
	s_add_i32 m0, s38, 0x2000
	s_nop 0
	global_load_lds_dwordx4 v[196:197], off
	v_lshl_add_u64 v[196:197], v[234:235], 0, s[64:65]
	s_mov_b32 m0, s12
	s_nop 0
	global_load_lds_dwordx4 v[196:197], off
	v_lshl_add_u64 v[196:197], v[236:237], 0, s[64:65]
	s_mov_b32 m0, s13
	s_nop 0
	global_load_lds_dwordx4 v[196:197], off
	s_waitcnt vmcnt(8)
	s_waitcnt lgkmcnt(0)
	s_barrier
	s_waitcnt lgkmcnt(0)
	v_mfma_f32_16x16x32_bf16 v[30:33], v[156:159], v[188:191], v[30:33]
	v_mfma_f32_16x16x32_bf16 v[26:29], v[164:167], v[188:191], v[26:29]
	v_mfma_f32_16x16x32_bf16 v[22:25], v[156:159], v[200:203], v[22:25]
	v_mfma_f32_16x16x32_bf16 v[18:21], v[164:167], v[200:203], v[18:21]
	v_mfma_f32_16x16x32_bf16 v[14:17], v[156:159], v[216:219], v[14:17]
	v_mfma_f32_16x16x32_bf16 v[10:13], v[164:167], v[216:219], v[10:13]
	v_mfma_f32_16x16x32_bf16 v[6:9], v[156:159], v[224:227], v[6:9]
	v_mfma_f32_16x16x32_bf16 v[2:5], v[164:167], v[224:227], v[2:5]
	v_mfma_f32_16x16x32_bf16 v[30:33], v[160:163], v[192:195], v[30:33]
	v_mfma_f32_16x16x32_bf16 v[26:29], v[168:171], v[192:195], v[26:29]
	v_mfma_f32_16x16x32_bf16 v[22:25], v[160:163], v[204:207], v[22:25]
	v_mfma_f32_16x16x32_bf16 v[18:21], v[168:171], v[204:207], v[18:21]
	v_mfma_f32_16x16x32_bf16 v[14:17], v[160:163], v[220:223], v[14:17]
	v_mfma_f32_16x16x32_bf16 v[10:13], v[168:171], v[220:223], v[10:13]
	v_mfma_f32_16x16x32_bf16 v[6:9], v[160:163], v[228:231], v[6:9]
	v_mfma_f32_16x16x32_bf16 v[2:5], v[168:171], v[228:231], v[2:5]
	v_mfma_f32_16x16x32_bf16 v[98:101], v[172:175], v[188:191], v[98:101]
	v_mfma_f32_16x16x32_bf16 v[102:105], v[180:183], v[188:191], v[102:105]
	v_mfma_f32_16x16x32_bf16 v[106:109], v[172:175], v[200:203], v[106:109]
	v_mfma_f32_16x16x32_bf16 v[110:113], v[180:183], v[200:203], v[110:113]
	v_mfma_f32_16x16x32_bf16 v[114:117], v[172:175], v[216:219], v[114:117]
	v_mfma_f32_16x16x32_bf16 v[118:121], v[180:183], v[216:219], v[118:121]
	v_mfma_f32_16x16x32_bf16 v[122:125], v[172:175], v[224:227], v[122:125]
	v_mfma_f32_16x16x32_bf16 v[126:129], v[180:183], v[224:227], v[126:129]
	v_mfma_f32_16x16x32_bf16 v[98:101], v[176:179], v[192:195], v[98:101]
	v_mfma_f32_16x16x32_bf16 v[102:105], v[184:187], v[192:195], v[102:105]
	v_mfma_f32_16x16x32_bf16 v[106:109], v[176:179], v[204:207], v[106:109]
	v_mfma_f32_16x16x32_bf16 v[110:113], v[184:187], v[204:207], v[110:113]
	v_mfma_f32_16x16x32_bf16 v[114:117], v[176:179], v[220:223], v[114:117]
	v_mfma_f32_16x16x32_bf16 v[118:121], v[184:187], v[220:223], v[118:121]
	v_mfma_f32_16x16x32_bf16 v[122:125], v[176:179], v[228:231], v[122:125]
	v_mfma_f32_16x16x32_bf16 v[126:129], v[184:187], v[228:231], v[126:129]
	s_barrier
	s_add_i32 s51, s51, 2
	s_add_u32 s34, s34, 0x100
	s_addc_u32 s35, s35, 0
	s_cmp_gt_u32 s51, 13
	s_cbranch_scc0 .LBB0_380
	s_and_b64 vcc, exec, s[22:23]
	s_cbranch_vccz .LBB0_383
	s_barrier

; #define PG8_STAGE(bufoff, gbase, voff) do { _Pragma("unroll") for (int _i = 0; _i < 2; ++_i) \
;         __builtin_amdgcn_global_load_lds((const unsigned*)((const char*)(gbase) + (voff)[_i]), (LAS unsigned*)(lds + (bufoff) + ldsw + _i * 8192), 16, 0, 0); } while (0)
; #define PG8_LDA(dst, b, h) do { _Pragma("unroll") for (int m = 0; m < 4; ++m) _Pragma("unroll") for (int k = 0; k < 2; ++k) dst[m][k] = *(const LAS bf16x8*)(lds + PG8_SA(b, h) + aoff + m * 2048 + k * 1024); } while (0)
; #define PG8_LDB(dst, b, h) do { _Pragma("unroll") for (int n = 0; n < 2; ++n) _Pragma("unroll") for (int k = 0; k < 2; ++k) dst[n][k] = *(const LAS bf16x8*)(lds + PG8_SB(b, h) + boff + n * 2048 + k * 1024); } while (0)
; #define PG8_WAIT_V(n) asm volatile("s_waitcnt vmcnt(" #n ")" ::: "memory")
; #define PG8_BAR __builtin_amdgcn_s_barrier()
; template <class Epi>
; __device__ __forceinline__ void gemm_phase(LAS unsigned char* lds, const Gemm g, const StaticOrder& S, const Epi& E, const float* SS) {
;     ...
;         for (int t = 0; t < nt; t += 2) {
;             const bool last = (t == nt - 2);
;             const char* a1 = cA + (size_t)(t + 1) * kstep;
;             const char* a2 = last ? nA : cA + (size_t)(t + 2) * kstep; const char* b2 = last ? nB : cB + (size_t)(t + 2) * kstep;
;             const char* a3 = a2 + kstep; const char* b3 = b2 + kstep;
;             PG8_LDB(B0, 0, 0); PG8_LDB(B1, 0, 1); PG8_SCHED; PG8_LDA(At, 0, 0); PG8_STAGE(PG8_SA(1, 1), a1 + hstep, voffA);
;             PG8_WAIT_V(8); PG8_WAIT_L(0); PG8_BAR; PG8_MMA(0, 0, At, B0); PG8_MMA(0, 1, At, B1); PG8_BAR; PG8_SCHED;
;             PG8_LDA(At, 0, 1); PG8_STAGE(PG8_SB(0, 0), b2, voffB); PG8_STAGE(PG8_SB(0, 1), b2 + hstep, voffB); PG8_STAGE(PG8_SA(0, 0), a2, voffA);
;             PG8_WAIT_V(8); PG8_WAIT_L(0); PG8_BAR; PG8_MMA(1, 0, At, B0); PG8_MMA(1, 1, At, B1); PG8_BAR; PG8_SCHED;
;             PG8_LDB(B0, 1, 0); PG8_LDB(B1, 1, 1); PG8_SCHED; PG8_LDA(At, 1, 0); PG8_STAGE(PG8_SA(0, 1), a2 + hstep, voffA);
;             PG8_WAIT_V(8); PG8_WAIT_L(0); PG8_BAR; PG8_MMA(0, 0, At, B0); PG8_MMA(0, 1, At, B1); PG8_BAR; PG8_SCHED;
;             PG8_LDA(At, 1, 1); PG8_STAGE(PG8_SB(1, 0), b3, voffB); PG8_STAGE(PG8_SB(1, 1), b3 + hstep, voffB); PG8_STAGE(PG8_SA(1, 0), a3, voffA);
;             PG8_WAIT_V(8); PG8_WAIT_L(0); PG8_BAR; PG8_MMA(1, 0, At, B0); PG8_MMA(1, 1, At, B1); PG8_BAR; PG8_SCHED;
;         }
.LBB0_501:
	s_add_u32 s60, s40, s58
	s_addc_u32 s61, s41, s59
	s_add_u32 s60, s60, 0x100
	s_addc_u32 s61, s61, 0
	s_add_u32 s86, s4, s58
	s_addc_u32 s87, s5, s59
	s_add_i32 vcc_hi, 0, 0x10000
	s_cmpk_eq_i32 s58, 0x700
	s_cselect_b32 s69, s51, s61
	s_cselect_b32 s68, s52, s60
	v_add_u32_e32 v0, vcc_hi, v167
	s_cselect_b32 s61, s49, s87
	s_cselect_b32 s60, s53, s86
	s_add_i32 s6, 0, 0x14000
	ds_read_b128 v[134:137], v0
	ds_read_b128 v[150:153], v0 offset:1024
	ds_read_b128 v[154:157], v0 offset:2048
	ds_read_b128 v[158:161], v0 offset:3072
	v_add_u32_e32 v0, s6, v167
	ds_read_b128 v[162:165], v0
	ds_read_b128 v[178:181], v0 offset:1024
	ds_read_b128 v[182:185], v0 offset:2048
	ds_read_b128 v[186:189], v0 offset:3072
	v_lshl_add_u64 v[232:233], v[132:133], 0, s[58:59]
	s_add_i32 m0, s37, 0xc000
	ds_read_b128 v[190:193], v177
	ds_read_b128 v[194:197], v177 offset:1024
	ds_read_b128 v[200:203], v177 offset:2048
	ds_read_b128 v[204:207], v177 offset:3072
	ds_read_b128 v[216:219], v177 offset:4096
	ds_read_b128 v[220:223], v177 offset:5120
	ds_read_b128 v[224:227], v177 offset:6144
	ds_read_b128 v[228:231], v177 offset:7168
	global_load_lds_dwordx4 v[232:233], off
	v_lshl_add_u64 v[232:233], v[130:131], 0, s[58:59]
	s_add_i32 m0, s37, 0xe000
	s_nop 0
	global_load_lds_dwordx4 v[232:233], off
	s_waitcnt vmcnt(8)
	s_waitcnt lgkmcnt(0)
	s_barrier
	s_waitcnt lgkmcnt(0)
	v_mfma_f32_16x16x32_bf16 v[94:97], v[134:137], v[190:193], v[94:97]
	v_mfma_f32_16x16x32_bf16 v[90:93], v[154:157], v[190:193], v[90:93]
	v_mfma_f32_16x16x32_bf16 v[86:89], v[134:137], v[200:203], v[86:89]
	v_mfma_f32_16x16x32_bf16 v[82:85], v[154:157], v[200:203], v[82:85]
	v_mfma_f32_16x16x32_bf16 v[78:81], v[134:137], v[216:219], v[78:81]
	v_mfma_f32_16x16x32_bf16 v[74:77], v[154:157], v[216:219], v[74:77]
	v_mfma_f32_16x16x32_bf16 v[70:73], v[134:137], v[224:227], v[70:73]
	v_mfma_f32_16x16x32_bf16 v[66:69], v[154:157], v[224:227], v[66:69]
	v_mfma_f32_16x16x32_bf16 v[94:97], v[150:153], v[194:197], v[94:97]
	v_mfma_f32_16x16x32_bf16 v[90:93], v[158:161], v[194:197], v[90:93]
	v_mfma_f32_16x16x32_bf16 v[86:89], v[150:153], v[204:207], v[86:89]
	v_mfma_f32_16x16x32_bf16 v[82:85], v[158:161], v[204:207], v[82:85]
	v_mfma_f32_16x16x32_bf16 v[78:81], v[150:153], v[220:223], v[78:81]
	v_mfma_f32_16x16x32_bf16 v[74:77], v[158:161], v[220:223], v[74:77]
	v_mfma_f32_16x16x32_bf16 v[70:73], v[150:153], v[228:231], v[70:73]
	v_mfma_f32_16x16x32_bf16 v[66:69], v[158:161], v[228:231], v[66:69]
	v_mfma_f32_16x16x32_bf16 v[62:65], v[162:165], v[190:193], v[62:65]
	v_mfma_f32_16x16x32_bf16 v[58:61], v[182:185], v[190:193], v[58:61]
	v_mfma_f32_16x16x32_bf16 v[54:57], v[162:165], v[200:203], v[54:57]
	v_mfma_f32_16x16x32_bf16 v[50:53], v[182:185], v[200:203], v[50:53]
	v_mfma_f32_16x16x32_bf16 v[46:49], v[162:165], v[216:219], v[46:49]
	v_mfma_f32_16x16x32_bf16 v[42:45], v[182:185], v[216:219], v[42:45]
	v_mfma_f32_16x16x32_bf16 v[38:41], v[162:165], v[224:227], v[38:41]
	v_mfma_f32_16x16x32_bf16 v[34:37], v[182:185], v[224:227], v[34:37]
	v_mfma_f32_16x16x32_bf16 v[62:65], v[178:181], v[194:197], v[62:65]
	v_mfma_f32_16x16x32_bf16 v[58:61], v[186:189], v[194:197], v[58:61]
	v_mfma_f32_16x16x32_bf16 v[54:57], v[178:181], v[204:207], v[54:57]
	v_mfma_f32_16x16x32_bf16 v[50:53], v[186:189], v[204:207], v[50:53]
	v_mfma_f32_16x16x32_bf16 v[46:49], v[178:181], v[220:223], v[46:49]
	v_mfma_f32_16x16x32_bf16 v[42:45], v[186:189], v[220:223], v[42:45]
	v_mfma_f32_16x16x32_bf16 v[38:41], v[178:181], v[228:231], v[38:41]
	v_mfma_f32_16x16x32_bf16 v[34:37], v[186:189], v[228:231], v[34:37]
	s_barrier
	s_add_i32 s86, vcc_hi, s25
	v_lshl_add_u64 v[232:233], s[60:61], 0, v[140:141]
	s_mov_b32 m0, s86
	ds_read_b128 v[190:193], v177 offset:16384
	ds_read_b128 v[194:197], v177 offset:17408
	ds_read_b128 v[200:203], v177 offset:18432
	ds_read_b128 v[204:207], v177 offset:19456
	ds_read_b128 v[216:219], v177 offset:20480
	ds_read_b128 v[220:223], v177 offset:21504
	ds_read_b128 v[224:227], v177 offset:22528
	ds_read_b128 v[228:231], v177 offset:23552
	global_load_lds_dwordx4 v[232:233], off
	s_add_i32 m0, s86, 0x2000
	s_add_u32 s86, s60, 0x40000
	v_lshl_add_u64 v[234:235], s[60:61], 0, v[144:145]
	s_addc_u32 s87, s61, 0
	s_add_i32 s6, s6, s25
	global_load_lds_dwordx4 v[234:235], off
	v_lshl_add_u64 v[236:237], s[86:87], 0, v[140:141]
	s_mov_b32 m0, s6
	v_lshl_add_u64 v[238:239], s[68:69], 0, v[142:143]
	global_load_lds_dwordx4 v[236:237], off
	v_lshl_add_u64 v[236:237], s[86:87], 0, v[144:145]
	s_add_i32 m0, s6, 0x2000
	s_nop 0
	global_load_lds_dwordx4 v[236:237], off
	v_lshl_add_u64 v[236:237], s[68:69], 0, v[138:139]
	s_mov_b32 m0, s37
	s_nop 0
	global_load_lds_dwordx4 v[236:237], off
	s_mov_b32 m0, s39
	s_nop 0
	global_load_lds_dwordx4 v[238:239], off
	s_waitcnt vmcnt(8)
	s_waitcnt lgkmcnt(0)
	s_barrier
; #define PG8_STAGE(bufoff, gbase, voff) do { _Pragma("unroll") for (int _i = 0; _i < 2; ++_i) \
;         __builtin_amdgcn_global_load_lds((const unsigned*)((const char*)(gbase) + (voff)[_i]), (LAS unsigned*)(lds + (bufoff) + ldsw + _i * 8192), 16, 0, 0); } while (0)
; #define PG8_LDA(dst, b, h) do { _Pragma("unroll") for (int m = 0; m < 4; ++m) _Pragma("unroll") for (int k = 0; k < 2; ++k) dst[m][k] = *(const LAS bf16x8*)(lds + PG8_SA(b, h) + aoff + m * 2048 + k * 1024); } while (0)
; #define PG8_LDB(dst, b, h) do { _Pragma("unroll") for (int n = 0; n < 2; ++n) _Pragma("unroll") for (int k = 0; k < 2; ++k) dst[n][k] = *(const LAS bf16x8*)(lds + PG8_SB(b, h) + boff + n * 2048 + k * 1024); } while (0)
; #define PG8_WAIT_V(n) asm volatile("s_waitcnt vmcnt(" #n ")" ::: "memory")
; #define PG8_BAR __builtin_amdgcn_s_barrier()
; template <class Epi>
; __device__ __forceinline__ void gemm_phase(LAS unsigned char* lds, const Gemm g, const StaticOrder& S, const Epi& E, const float* SS) {
;     ...
;         for (int t = 0; t < nt; t += 2) {
;             const bool last = (t == nt - 2);
;             const char* a1 = cA + (size_t)(t + 1) * kstep;
;             const char* a2 = last ? nA : cA + (size_t)(t + 2) * kstep; const char* b2 = last ? nB : cB + (size_t)(t + 2) * kstep;
;             const char* a3 = a2 + kstep; const char* b3 = b2 + kstep;
;             PG8_LDB(B0, 0, 0); PG8_LDB(B1, 0, 1); PG8_SCHED; PG8_LDA(At, 0, 0); PG8_STAGE(PG8_SA(1, 1), a1 + hstep, voffA);
;             PG8_WAIT_V(8); PG8_WAIT_L(0); PG8_BAR; PG8_MMA(0, 0, At, B0); PG8_MMA(0, 1, At, B1); PG8_BAR; PG8_SCHED;
;             PG8_LDA(At, 0, 1); PG8_STAGE(PG8_SB(0, 0), b2, voffB); PG8_STAGE(PG8_SB(0, 1), b2 + hstep, voffB); PG8_STAGE(PG8_SA(0, 0), a2, voffA);
;             PG8_WAIT_V(8); PG8_WAIT_L(0); PG8_BAR; PG8_MMA(1, 0, At, B0); PG8_MMA(1, 1, At, B1); PG8_BAR; PG8_SCHED;
;             PG8_LDB(B0, 1, 0); PG8_LDB(B1, 1, 1); PG8_SCHED; PG8_LDA(At, 1, 0); PG8_STAGE(PG8_SA(0, 1), a2 + hstep, voffA);
;             PG8_WAIT_V(8); PG8_WAIT_L(0); PG8_BAR; PG8_MMA(0, 0, At, B0); PG8_MMA(0, 1, At, B1); PG8_BAR; PG8_SCHED;
;             PG8_LDA(At, 1, 1); PG8_STAGE(PG8_SB(1, 0), b3, voffB); PG8_STAGE(PG8_SB(1, 1), b3 + hstep, voffB); PG8_STAGE(PG8_SA(1, 0), a3, voffA);
;             PG8_WAIT_V(8); PG8_WAIT_L(0); PG8_BAR; PG8_MMA(1, 0, At, B0); PG8_MMA(1, 1, At, B1); PG8_BAR; PG8_SCHED;
;         }
	s_waitcnt lgkmcnt(0)
	v_mfma_f32_16x16x32_bf16 v[30:33], v[134:137], v[190:193], v[30:33]
	v_mfma_f32_16x16x32_bf16 v[26:29], v[154:157], v[190:193], v[26:29]
	v_mfma_f32_16x16x32_bf16 v[22:25], v[134:137], v[200:203], v[22:25]
	v_mfma_f32_16x16x32_bf16 v[18:21], v[154:157], v[200:203], v[18:21]
	v_mfma_f32_16x16x32_bf16 v[14:17], v[134:137], v[216:219], v[14:17]
	v_mfma_f32_16x16x32_bf16 v[10:13], v[154:157], v[216:219], v[10:13]
	v_mfma_f32_16x16x32_bf16 v[6:9], v[134:137], v[224:227], v[6:9]
	v_mfma_f32_16x16x32_bf16 v[2:5], v[154:157], v[224:227], v[2:5]
	v_mfma_f32_16x16x32_bf16 v[30:33], v[150:153], v[194:197], v[30:33]
	v_mfma_f32_16x16x32_bf16 v[26:29], v[158:161], v[194:197], v[26:29]
	v_mfma_f32_16x16x32_bf16 v[22:25], v[150:153], v[204:207], v[22:25]
	v_mfma_f32_16x16x32_bf16 v[18:21], v[158:161], v[204:207], v[18:21]
	v_mfma_f32_16x16x32_bf16 v[14:17], v[150:153], v[220:223], v[14:17]
	v_mfma_f32_16x16x32_bf16 v[10:13], v[158:161], v[220:223], v[10:13]
	v_mfma_f32_16x16x32_bf16 v[6:9], v[150:153], v[228:231], v[6:9]
	v_mfma_f32_16x16x32_bf16 v[2:5], v[158:161], v[228:231], v[2:5]
	v_mfma_f32_16x16x32_bf16 v[98:101], v[162:165], v[190:193], v[98:101]
	v_mfma_f32_16x16x32_bf16 v[102:105], v[182:185], v[190:193], v[102:105]
	v_mfma_f32_16x16x32_bf16 v[106:109], v[162:165], v[200:203], v[106:109]
	v_mfma_f32_16x16x32_bf16 v[110:113], v[182:185], v[200:203], v[110:113]
	v_mfma_f32_16x16x32_bf16 v[114:117], v[162:165], v[216:219], v[114:117]
	v_mfma_f32_16x16x32_bf16 v[118:121], v[182:185], v[216:219], v[118:121]
	v_mfma_f32_16x16x32_bf16 v[122:125], v[162:165], v[224:227], v[122:125]
	v_mfma_f32_16x16x32_bf16 v[126:129], v[182:185], v[224:227], v[126:129]
	v_mfma_f32_16x16x32_bf16 v[98:101], v[178:181], v[194:197], v[98:101]
	v_mfma_f32_16x16x32_bf16 v[102:105], v[186:189], v[194:197], v[102:105]
	v_mfma_f32_16x16x32_bf16 v[106:109], v[178:181], v[204:207], v[106:109]
	v_mfma_f32_16x16x32_bf16 v[110:113], v[186:189], v[204:207], v[110:113]
	v_mfma_f32_16x16x32_bf16 v[114:117], v[178:181], v[220:223], v[114:117]
	v_mfma_f32_16x16x32_bf16 v[118:121], v[186:189], v[220:223], v[118:121]
	v_mfma_f32_16x16x32_bf16 v[122:125], v[178:181], v[228:231], v[122:125]
	v_mfma_f32_16x16x32_bf16 v[126:129], v[186:189], v[228:231], v[126:129]
	s_barrier
	s_add_i32 s6, 0, 0x18000
	v_add_u32_e32 v0, s6, v167
	s_add_i32 s86, 0, 0x1c000
	ds_read_b128 v[134:137], v0
	ds_read_b128 v[150:153], v0 offset:1024
	ds_read_b128 v[154:157], v0 offset:2048
	ds_read_b128 v[158:161], v0 offset:3072
	v_add_u32_e32 v0, s86, v167
	ds_read_b128 v[162:165], v0
	ds_read_b128 v[178:181], v0 offset:1024
	ds_read_b128 v[182:185], v0 offset:2048
	ds_read_b128 v[186:189], v0 offset:3072
	s_add_u32 s68, s68, 0x40000
	s_addc_u32 s69, s69, 0
	s_mov_b32 m0, s14
	v_lshl_add_u64 v[240:241], s[68:69], 0, v[138:139]
	ds_read_b128 v[190:193], v177 offset:32768
	ds_read_b128 v[194:197], v177 offset:33792
	ds_read_b128 v[200:203], v177 offset:34816
	ds_read_b128 v[204:207], v177 offset:35840
	ds_read_b128 v[216:219], v177 offset:36864
	ds_read_b128 v[220:223], v177 offset:37888
	ds_read_b128 v[224:227], v177 offset:38912
	ds_read_b128 v[228:231], v177 offset:39936
	global_load_lds_dwordx4 v[240:241], off
	v_lshl_add_u64 v[240:241], s[68:69], 0, v[142:143]
	s_mov_b32 m0, s15
	s_nop 0
	global_load_lds_dwordx4 v[240:241], off
	s_waitcnt vmcnt(8)
	s_waitcnt lgkmcnt(0)
	s_barrier
	s_waitcnt lgkmcnt(0)
	v_mfma_f32_16x16x32_bf16 v[94:97], v[134:137], v[190:193], v[94:97]
	v_mfma_f32_16x16x32_bf16 v[90:93], v[154:157], v[190:193], v[90:93]
	v_mfma_f32_16x16x32_bf16 v[86:89], v[134:137], v[200:203], v[86:89]
	v_mfma_f32_16x16x32_bf16 v[82:85], v[154:157], v[200:203], v[82:85]
	v_mfma_f32_16x16x32_bf16 v[78:81], v[134:137], v[216:219], v[78:81]
	v_mfma_f32_16x16x32_bf16 v[74:77], v[154:157], v[216:219], v[74:77]
	v_mfma_f32_16x16x32_bf16 v[70:73], v[134:137], v[224:227], v[70:73]
	v_mfma_f32_16x16x32_bf16 v[66:69], v[154:157], v[224:227], v[66:69]
	v_mfma_f32_16x16x32_bf16 v[94:97], v[150:153], v[194:197], v[94:97]
	v_mfma_f32_16x16x32_bf16 v[90:93], v[158:161], v[194:197], v[90:93]
	v_mfma_f32_16x16x32_bf16 v[86:89], v[150:153], v[204:207], v[86:89]
	v_mfma_f32_16x16x32_bf16 v[82:85], v[158:161], v[204:207], v[82:85]
	v_mfma_f32_16x16x32_bf16 v[78:81], v[150:153], v[220:223], v[78:81]
	v_mfma_f32_16x16x32_bf16 v[74:77], v[158:161], v[220:223], v[74:77]
	v_mfma_f32_16x16x32_bf16 v[70:73], v[150:153], v[228:231], v[70:73]
	v_mfma_f32_16x16x32_bf16 v[66:69], v[158:161], v[228:231], v[66:69]
	v_mfma_f32_16x16x32_bf16 v[62:65], v[162:165], v[190:193], v[62:65]
	v_mfma_f32_16x16x32_bf16 v[58:61], v[182:185], v[190:193], v[58:61]
	v_mfma_f32_16x16x32_bf16 v[54:57], v[162:165], v[200:203], v[54:57]
	v_mfma_f32_16x16x32_bf16 v[50:53], v[182:185], v[200:203], v[50:53]
	v_mfma_f32_16x16x32_bf16 v[46:49], v[162:165], v[216:219], v[46:49]
	v_mfma_f32_16x16x32_bf16 v[42:45], v[182:185], v[216:219], v[42:45]
	v_mfma_f32_16x16x32_bf16 v[38:41], v[162:165], v[224:227], v[38:41]
	v_mfma_f32_16x16x32_bf16 v[34:37], v[182:185], v[224:227], v[34:37]
	v_mfma_f32_16x16x32_bf16 v[62:65], v[178:181], v[194:197], v[62:65]
	v_mfma_f32_16x16x32_bf16 v[58:61], v[186:189], v[194:197], v[58:61]
	v_mfma_f32_16x16x32_bf16 v[54:57], v[178:181], v[204:207], v[54:57]
	v_mfma_f32_16x16x32_bf16 v[50:53], v[186:189], v[204:207], v[50:53]
	v_mfma_f32_16x16x32_bf16 v[46:49], v[178:181], v[220:223], v[46:49]
	v_mfma_f32_16x16x32_bf16 v[42:45], v[186:189], v[220:223], v[42:45]
	v_mfma_f32_16x16x32_bf16 v[38:41], v[178:181], v[228:231], v[38:41]
	v_mfma_f32_16x16x32_bf16 v[34:37], v[186:189], v[228:231], v[34:37]
	s_barrier
; #define PG8_STAGE(bufoff, gbase, voff) do { _Pragma("unroll") for (int _i = 0; _i < 2; ++_i) \
;         __builtin_amdgcn_global_load_lds((const unsigned*)((const char*)(gbase) + (voff)[_i]), (LAS unsigned*)(lds + (bufoff) + ldsw + _i * 8192), 16, 0, 0); } while (0)
; #define PG8_LDA(dst, b, h) do { _Pragma("unroll") for (int m = 0; m < 4; ++m) _Pragma("unroll") for (int k = 0; k < 2; ++k) dst[m][k] = *(const LAS bf16x8*)(lds + PG8_SA(b, h) + aoff + m * 2048 + k * 1024); } while (0)
; #define PG8_LDB(dst, b, h) do { _Pragma("unroll") for (int n = 0; n < 2; ++n) _Pragma("unroll") for (int k = 0; k < 2; ++k) dst[n][k] = *(const LAS bf16x8*)(lds + PG8_SB(b, h) + boff + n * 2048 + k * 1024); } while (0)
; #define PG8_MMA(ai, bj, At, Bt) do { __builtin_amdgcn_s_setprio(1); _Pragma("unroll") for (int m = 0; m < 4; ++m) _Pragma("unroll") for (int n = 0; n < 2; ++n) _Pragma("unroll") for (int k = 0; k < 2; ++k) \
;         acc[ai][bj][m][n] = __builtin_amdgcn_mfma_f32_16x16x32_bf16(Bt[n][k], At[m][k], acc[ai][bj][m][n], 0, 0, 0); __builtin_amdgcn_s_setprio(0); } while (0)
; #define PG8_WAIT_V(n) asm volatile("s_waitcnt vmcnt(" #n ")" ::: "memory")
; template <class Epi>
; __device__ __forceinline__ void gemm_phase(LAS unsigned char* lds, const Gemm g, const StaticOrder& S, const Epi& E, const float* SS) {
;     ...
;             PG8_LDB(B0, 0, 0); PG8_LDB(B1, 0, 1); PG8_SCHED; PG8_LDA(At, 0, 0); PG8_STAGE(PG8_SA(1, 1), a1 + hstep, voffA);
;             PG8_WAIT_V(8); PG8_WAIT_L(0); PG8_BAR; PG8_MMA(0, 0, At, B0); PG8_MMA(0, 1, At, B1); PG8_BAR; PG8_SCHED;
;             PG8_LDA(At, 0, 1); PG8_STAGE(PG8_SB(0, 0), b2, voffB); PG8_STAGE(PG8_SB(0, 1), b2 + hstep, voffB); PG8_STAGE(PG8_SA(0, 0), a2, voffA);
;             PG8_WAIT_V(8); PG8_WAIT_L(0); PG8_BAR; PG8_MMA(1, 0, At, B0); PG8_MMA(1, 1, At, B1); PG8_BAR; PG8_SCHED;
;             PG8_LDB(B0, 1, 0); PG8_LDB(B1, 1, 1); PG8_SCHED; PG8_LDA(At, 1, 0); PG8_STAGE(PG8_SA(0, 1), a2 + hstep, voffA);
;             PG8_WAIT_V(8); PG8_WAIT_L(0); PG8_BAR; PG8_MMA(0, 0, At, B0); PG8_MMA(0, 1, At, B1); PG8_BAR; PG8_SCHED;
;             PG8_LDA(At, 1, 1); PG8_STAGE(PG8_SB(1, 0), b3, voffB); PG8_STAGE(PG8_SB(1, 1), b3 + hstep, voffB); PG8_STAGE(PG8_SA(1, 0), a3, voffA);
;             PG8_WAIT_V(8); PG8_WAIT_L(0); PG8_BAR; PG8_MMA(1, 0, At, B0); PG8_MMA(1, 1, At, B1); PG8_BAR; PG8_SCHED;
;         }
;         if (wr == 0) PG8_BAR;
	s_add_i32 s6, s6, s25
	v_lshl_add_u64 v[232:233], v[232:233], 0, s[64:65]
	s_mov_b32 m0, s6
	ds_read_b128 v[190:193], v177 offset:49152
	ds_read_b128 v[194:197], v177 offset:50176
	ds_read_b128 v[200:203], v177 offset:51200
	ds_read_b128 v[204:207], v177 offset:52224
	ds_read_b128 v[216:219], v177 offset:53248
	ds_read_b128 v[220:223], v177 offset:54272
	ds_read_b128 v[224:227], v177 offset:55296
	ds_read_b128 v[228:231], v177 offset:56320
	global_load_lds_dwordx4 v[232:233], off
	s_add_i32 m0, s6, 0x2000
	s_add_u32 s60, s60, 0x40080
	v_lshl_add_u64 v[232:233], v[234:235], 0, s[64:65]
	s_addc_u32 s61, s61, 0
	s_add_i32 s6, s86, s25
	global_load_lds_dwordx4 v[232:233], off
	v_lshl_add_u64 v[232:233], s[60:61], 0, v[140:141]
	s_mov_b32 m0, s6
	s_nop 0
	global_load_lds_dwordx4 v[232:233], off
	v_lshl_add_u64 v[232:233], s[60:61], 0, v[144:145]
	s_add_i32 m0, s6, 0x2000
	s_nop 0
	global_load_lds_dwordx4 v[232:233], off
	v_lshl_add_u64 v[232:233], v[236:237], 0, s[64:65]
	s_mov_b32 m0, s89
	s_nop 0
	global_load_lds_dwordx4 v[232:233], off
	v_lshl_add_u64 v[232:233], v[238:239], 0, s[64:65]
	s_mov_b32 m0, s88
	s_nop 0
	global_load_lds_dwordx4 v[232:233], off
	s_waitcnt vmcnt(8)
	s_waitcnt lgkmcnt(0)
	s_barrier
	s_waitcnt lgkmcnt(0)
	v_mfma_f32_16x16x32_bf16 v[30:33], v[134:137], v[190:193], v[30:33]
	v_mfma_f32_16x16x32_bf16 v[26:29], v[154:157], v[190:193], v[26:29]
	v_mfma_f32_16x16x32_bf16 v[22:25], v[134:137], v[200:203], v[22:25]
	v_mfma_f32_16x16x32_bf16 v[18:21], v[154:157], v[200:203], v[18:21]
	v_mfma_f32_16x16x32_bf16 v[14:17], v[134:137], v[216:219], v[14:17]
	v_mfma_f32_16x16x32_bf16 v[10:13], v[154:157], v[216:219], v[10:13]
	v_mfma_f32_16x16x32_bf16 v[6:9], v[134:137], v[224:227], v[6:9]
	v_mfma_f32_16x16x32_bf16 v[2:5], v[154:157], v[224:227], v[2:5]
	v_mfma_f32_16x16x32_bf16 v[30:33], v[150:153], v[194:197], v[30:33]
	v_mfma_f32_16x16x32_bf16 v[26:29], v[158:161], v[194:197], v[26:29]
	v_mfma_f32_16x16x32_bf16 v[22:25], v[150:153], v[204:207], v[22:25]
	v_mfma_f32_16x16x32_bf16 v[18:21], v[158:161], v[204:207], v[18:21]
	v_mfma_f32_16x16x32_bf16 v[14:17], v[150:153], v[220:223], v[14:17]
	v_mfma_f32_16x16x32_bf16 v[10:13], v[158:161], v[220:223], v[10:13]
	v_mfma_f32_16x16x32_bf16 v[6:9], v[150:153], v[228:231], v[6:9]
	v_mfma_f32_16x16x32_bf16 v[2:5], v[158:161], v[228:231], v[2:5]
	v_mfma_f32_16x16x32_bf16 v[98:101], v[162:165], v[190:193], v[98:101]
	v_mfma_f32_16x16x32_bf16 v[102:105], v[182:185], v[190:193], v[102:105]
	v_mfma_f32_16x16x32_bf16 v[106:109], v[162:165], v[200:203], v[106:109]
	v_mfma_f32_16x16x32_bf16 v[110:113], v[182:185], v[200:203], v[110:113]
	v_mfma_f32_16x16x32_bf16 v[114:117], v[162:165], v[216:219], v[114:117]
	v_mfma_f32_16x16x32_bf16 v[118:121], v[182:185], v[216:219], v[118:121]
	v_mfma_f32_16x16x32_bf16 v[122:125], v[162:165], v[224:227], v[122:125]
	v_mfma_f32_16x16x32_bf16 v[126:129], v[182:185], v[224:227], v[126:129]
	v_mfma_f32_16x16x32_bf16 v[98:101], v[178:181], v[194:197], v[98:101]
	v_mfma_f32_16x16x32_bf16 v[102:105], v[186:189], v[194:197], v[102:105]
	v_mfma_f32_16x16x32_bf16 v[106:109], v[178:181], v[204:207], v[106:109]
	v_mfma_f32_16x16x32_bf16 v[110:113], v[186:189], v[204:207], v[110:113]
	v_mfma_f32_16x16x32_bf16 v[114:117], v[178:181], v[220:223], v[114:117]
	v_mfma_f32_16x16x32_bf16 v[118:121], v[186:189], v[220:223], v[118:121]
	v_mfma_f32_16x16x32_bf16 v[122:125], v[178:181], v[228:231], v[122:125]
	v_mfma_f32_16x16x32_bf16 v[126:129], v[186:189], v[228:231], v[126:129]
	s_barrier
	s_add_i32 vcc_lo, vcc_lo, 2
	s_add_u32 s58, s58, 0x100
	s_addc_u32 s59, s59, 0
	s_cmp_gt_u32 vcc_lo, 13
	s_cbranch_scc0 .LBB0_501
	s_and_b64 vcc, exec, s[44:45]
	s_cbranch_vccz .LBB0_504
	s_barrier

; #define PG8_STAGE(bufoff, gbase, voff) do { _Pragma("unroll") for (int _i = 0; _i < 2; ++_i) \
;         __builtin_amdgcn_global_load_lds((const unsigned*)((const char*)(gbase) + (voff)[_i]), (LAS unsigned*)(lds + (bufoff) + ldsw + _i * 8192), 16, 0, 0); } while (0)
; #define PG8_LDA(dst, b, h) do { _Pragma("unroll") for (int m = 0; m < 4; ++m) _Pragma("unroll") for (int k = 0; k < 2; ++k) dst[m][k] = *(const LAS bf16x8*)(lds + PG8_SA(b, h) + aoff + m * 2048 + k * 1024); } while (0)
; #define PG8_LDB(dst, b, h) do { _Pragma("unroll") for (int n = 0; n < 2; ++n) _Pragma("unroll") for (int k = 0; k < 2; ++k) dst[n][k] = *(const LAS bf16x8*)(lds + PG8_SB(b, h) + boff + n * 2048 + k * 1024); } while (0)
; #define PG8_MMA(ai, bj, At, Bt) do { __builtin_amdgcn_s_setprio(1); _Pragma("unroll") for (int m = 0; m < 4; ++m) _Pragma("unroll") for (int n = 0; n < 2; ++n) _Pragma("unroll") for (int k = 0; k < 2; ++k) \
;         acc[ai][bj][m][n] = __builtin_amdgcn_mfma_f32_16x16x32_bf16(Bt[n][k], At[m][k], acc[ai][bj][m][n], 0, 0, 0); __builtin_amdgcn_s_setprio(0); } while (0)
; #define PG8_WAIT_V(n) asm volatile("s_waitcnt vmcnt(" #n ")" ::: "memory")
; #define PG8_WAIT_L(n) asm volatile("s_waitcnt lgkmcnt(" #n ")" ::: "memory")
; #define PG8_BAR __builtin_amdgcn_s_barrier()
; #define PG8_SCHED __builtin_amdgcn_sched_barrier(0)
; template <class Epi>
; __device__ __forceinline__ void gemm_phase(LAS unsigned char* lds, const Gemm g, const StaticOrder& S, const Epi& E, const float* SS) {
;     ...
;         for (int t = 0; t < nt; t += 2) {
;             const bool last = (t == nt - 2);
;             const char* a1 = cA + (size_t)(t + 1) * kstep;
;             const char* a2 = last ? nA : cA + (size_t)(t + 2) * kstep; const char* b2 = last ? nB : cB + (size_t)(t + 2) * kstep;
;             const char* a3 = a2 + kstep; const char* b3 = b2 + kstep;
;             PG8_LDB(B0, 0, 0); PG8_LDB(B1, 0, 1); PG8_SCHED; PG8_LDA(At, 0, 0); PG8_STAGE(PG8_SA(1, 1), a1 + hstep, voffA);
;             PG8_WAIT_V(8); PG8_WAIT_L(0); PG8_BAR; PG8_MMA(0, 0, At, B0); PG8_MMA(0, 1, At, B1); PG8_BAR; PG8_SCHED;
;             PG8_LDA(At, 0, 1); PG8_STAGE(PG8_SB(0, 0), b2, voffB); PG8_STAGE(PG8_SB(0, 1), b2 + hstep, voffB); PG8_STAGE(PG8_SA(0, 0), a2, voffA);
;             PG8_WAIT_V(8); PG8_WAIT_L(0); PG8_BAR; PG8_MMA(1, 0, At, B0); PG8_MMA(1, 1, At, B1); PG8_BAR; PG8_SCHED;
.LBB0_640:
	s_add_i32 s68, s44, 2
	s_add_u32 s6, s42, 0x80
	s_addc_u32 s45, s43, 0
	s_add_i32 s69, 0, 0x10000
	s_cmp_eq_u32 s54, s44
	s_cselect_b32 s45, s5, s45
	s_cselect_b32 s44, s4, s6
	s_cselect_b32 s87, s41, s61
	s_cselect_b32 s86, s40, s60
	s_add_i32 s6, 0, 0x14000
	v_add_u32_e32 v126, s69, v230
	v_add_u32_e32 v150, s6, v230
	ds_read_b128 v[106:109], v126
	ds_read_b128 v[110:113], v126 offset:1024
	ds_read_b128 v[122:125], v126 offset:2048
	ds_read_b128 v[126:129], v126 offset:3072
	ds_read_b128 v[138:141], v150
	ds_read_b128 v[142:145], v150 offset:1024
	ds_read_b128 v[146:149], v150 offset:2048
	ds_read_b128 v[150:153], v150 offset:3072
	v_lshl_add_u64 v[216:217], s[42:43], 0, v[202:203]
	s_add_i32 m0, s16, 0xc000
	ds_read_b128 v[162:165], v231
	ds_read_b128 v[166:169], v231 offset:1024
	ds_read_b128 v[170:173], v231 offset:2048
	ds_read_b128 v[174:177], v231 offset:3072
	ds_read_b128 v[178:181], v231 offset:4096
	ds_read_b128 v[182:185], v231 offset:5120
	ds_read_b128 v[186:189], v231 offset:6144
	ds_read_b128 v[204:207], v231 offset:7168
	global_load_lds_dwordx4 v[216:217], off
	v_lshl_add_u64 v[216:217], s[42:43], 0, v[200:201]
	s_add_i32 m0, s16, 0xe000
	s_nop 0
	global_load_lds_dwordx4 v[216:217], off
	s_waitcnt vmcnt(8)
	s_waitcnt lgkmcnt(0)
	s_barrier
	s_waitcnt lgkmcnt(0)
	v_mfma_f32_16x16x32_bf16 v[158:161], v[106:109], v[162:165], v[158:161]
	v_mfma_f32_16x16x32_bf16 v[154:157], v[122:125], v[162:165], v[154:157]
	v_mfma_f32_16x16x32_bf16 v[118:121], v[106:109], v[170:173], v[118:121]
	v_mfma_f32_16x16x32_bf16 v[114:117], v[122:125], v[170:173], v[114:117]
	v_mfma_f32_16x16x32_bf16 v[94:97], v[106:109], v[178:181], v[94:97]
	v_mfma_f32_16x16x32_bf16 v[90:93], v[122:125], v[178:181], v[90:93]
	v_mfma_f32_16x16x32_bf16 v[78:81], v[106:109], v[186:189], v[78:81]
	v_mfma_f32_16x16x32_bf16 v[74:77], v[122:125], v[186:189], v[74:77]
	v_mfma_f32_16x16x32_bf16 v[158:161], v[110:113], v[166:169], v[158:161]
	v_mfma_f32_16x16x32_bf16 v[154:157], v[126:129], v[166:169], v[154:157]
	v_mfma_f32_16x16x32_bf16 v[118:121], v[110:113], v[174:177], v[118:121]
	v_mfma_f32_16x16x32_bf16 v[114:117], v[126:129], v[174:177], v[114:117]
	v_mfma_f32_16x16x32_bf16 v[94:97], v[110:113], v[182:185], v[94:97]
	v_mfma_f32_16x16x32_bf16 v[90:93], v[126:129], v[182:185], v[90:93]
	v_mfma_f32_16x16x32_bf16 v[78:81], v[110:113], v[204:207], v[78:81]
	v_mfma_f32_16x16x32_bf16 v[74:77], v[126:129], v[204:207], v[74:77]
	v_mfma_f32_16x16x32_bf16 v[134:137], v[138:141], v[162:165], v[134:137]
	v_mfma_f32_16x16x32_bf16 v[130:133], v[146:149], v[162:165], v[130:133]
	v_mfma_f32_16x16x32_bf16 v[102:105], v[138:141], v[170:173], v[102:105]
	v_mfma_f32_16x16x32_bf16 v[98:101], v[146:149], v[170:173], v[98:101]
	v_mfma_f32_16x16x32_bf16 v[86:89], v[138:141], v[178:181], v[86:89]
	v_mfma_f32_16x16x32_bf16 v[82:85], v[146:149], v[178:181], v[82:85]
	v_mfma_f32_16x16x32_bf16 v[70:73], v[138:141], v[186:189], v[70:73]
	v_mfma_f32_16x16x32_bf16 v[66:69], v[146:149], v[186:189], v[66:69]
	v_mfma_f32_16x16x32_bf16 v[134:137], v[142:145], v[166:169], v[134:137]
	v_mfma_f32_16x16x32_bf16 v[130:133], v[150:153], v[166:169], v[130:133]
	v_mfma_f32_16x16x32_bf16 v[102:105], v[142:145], v[174:177], v[102:105]
	v_mfma_f32_16x16x32_bf16 v[98:101], v[150:153], v[174:177], v[98:101]
	v_mfma_f32_16x16x32_bf16 v[86:89], v[142:145], v[182:185], v[86:89]
	v_mfma_f32_16x16x32_bf16 v[82:85], v[150:153], v[182:185], v[82:85]
	v_mfma_f32_16x16x32_bf16 v[70:73], v[142:145], v[204:207], v[70:73]
	v_mfma_f32_16x16x32_bf16 v[66:69], v[150:153], v[204:207], v[66:69]
	s_barrier
	s_add_i32 s69, s69, s15
	v_lshl_add_u64 v[216:217], s[86:87], 0, v[192:193]
	s_mov_b32 m0, s69
	ds_read_b128 v[162:165], v231 offset:16384
	ds_read_b128 v[166:169], v231 offset:17408
	ds_read_b128 v[170:173], v231 offset:18432
	ds_read_b128 v[174:177], v231 offset:19456
	ds_read_b128 v[178:181], v231 offset:20480
	ds_read_b128 v[182:185], v231 offset:21504
	ds_read_b128 v[186:189], v231 offset:22528
	ds_read_b128 v[204:207], v231 offset:23552
	global_load_lds_dwordx4 v[216:217], off
	s_add_i32 m0, s69, 0x2000
	v_lshl_add_u64 v[218:219], s[86:87], 0, v[196:197]
	s_add_u32 s86, s86, s30
	s_addc_u32 s87, s87, 0
	s_add_i32 s6, s6, s15
	global_load_lds_dwordx4 v[218:219], off
	v_lshl_add_u64 v[220:221], s[86:87], 0, v[192:193]
	s_mov_b32 m0, s6
	v_lshl_add_u64 v[222:223], s[86:87], 0, v[196:197]
	global_load_lds_dwordx4 v[220:221], off
	s_add_i32 m0, s6, 0x2000
	v_lshl_add_u64 v[224:225], s[44:45], 0, v[190:191]
	global_load_lds_dwordx4 v[222:223], off
	s_mov_b32 m0, s16
	v_lshl_add_u64 v[226:227], s[44:45], 0, v[194:195]
	global_load_lds_dwordx4 v[224:225], off
	s_mov_b32 m0, s17
	s_nop 0
	global_load_lds_dwordx4 v[226:227], off
	s_waitcnt vmcnt(8)
	s_waitcnt lgkmcnt(0)
	s_barrier
; #define PG8_STAGE(bufoff, gbase, voff) do { _Pragma("unroll") for (int _i = 0; _i < 2; ++_i) \
;         __builtin_amdgcn_global_load_lds((const unsigned*)((const char*)(gbase) + (voff)[_i]), (LAS unsigned*)(lds + (bufoff) + ldsw + _i * 8192), 16, 0, 0); } while (0)
; #define PG8_LDA(dst, b, h) do { _Pragma("unroll") for (int m = 0; m < 4; ++m) _Pragma("unroll") for (int k = 0; k < 2; ++k) dst[m][k] = *(const LAS bf16x8*)(lds + PG8_SA(b, h) + aoff + m * 2048 + k * 1024); } while (0)
; #define PG8_LDB(dst, b, h) do { _Pragma("unroll") for (int n = 0; n < 2; ++n) _Pragma("unroll") for (int k = 0; k < 2; ++k) dst[n][k] = *(const LAS bf16x8*)(lds + PG8_SB(b, h) + boff + n * 2048 + k * 1024); } while (0)
; #define PG8_MMA(ai, bj, At, Bt) do { __builtin_amdgcn_s_setprio(1); _Pragma("unroll") for (int m = 0; m < 4; ++m) _Pragma("unroll") for (int n = 0; n < 2; ++n) _Pragma("unroll") for (int k = 0; k < 2; ++k) \
;         acc[ai][bj][m][n] = __builtin_amdgcn_mfma_f32_16x16x32_bf16(Bt[n][k], At[m][k], acc[ai][bj][m][n], 0, 0, 0); __builtin_amdgcn_s_setprio(0); } while (0)
; #define PG8_WAIT_V(n) asm volatile("s_waitcnt vmcnt(" #n ")" ::: "memory")
; #define PG8_WAIT_L(n) asm volatile("s_waitcnt lgkmcnt(" #n ")" ::: "memory")
; #define PG8_BAR __builtin_amdgcn_s_barrier()
; #define PG8_SCHED __builtin_amdgcn_sched_barrier(0)
; template <class Epi>
; __device__ __forceinline__ void gemm_phase(LAS unsigned char* lds, const Gemm g, const StaticOrder& S, const Epi& E, const float* SS) {
;     ...
;             PG8_WAIT_V(8); PG8_WAIT_L(0); PG8_BAR; PG8_MMA(1, 0, At, B0); PG8_MMA(1, 1, At, B1); PG8_BAR; PG8_SCHED;
;             PG8_LDB(B0, 1, 0); PG8_LDB(B1, 1, 1); PG8_SCHED; PG8_LDA(At, 1, 0); PG8_STAGE(PG8_SA(0, 1), a2 + hstep, voffA);
;             PG8_WAIT_V(8); PG8_WAIT_L(0); PG8_BAR; PG8_MMA(0, 0, At, B0); PG8_MMA(0, 1, At, B1); PG8_BAR; PG8_SCHED;
	s_waitcnt lgkmcnt(0)
	v_mfma_f32_16x16x32_bf16 v[62:65], v[106:109], v[162:165], v[62:65]
	v_mfma_f32_16x16x32_bf16 v[58:61], v[122:125], v[162:165], v[58:61]
	v_mfma_f32_16x16x32_bf16 v[46:49], v[106:109], v[170:173], v[46:49]
	v_mfma_f32_16x16x32_bf16 v[42:45], v[122:125], v[170:173], v[42:45]
	v_mfma_f32_16x16x32_bf16 v[30:33], v[106:109], v[178:181], v[30:33]
	v_mfma_f32_16x16x32_bf16 v[26:29], v[122:125], v[178:181], v[26:29]
	v_mfma_f32_16x16x32_bf16 v[14:17], v[106:109], v[186:189], v[14:17]
	v_mfma_f32_16x16x32_bf16 v[10:13], v[122:125], v[186:189], v[10:13]
	v_mfma_f32_16x16x32_bf16 v[62:65], v[110:113], v[166:169], v[62:65]
	v_mfma_f32_16x16x32_bf16 v[58:61], v[126:129], v[166:169], v[58:61]
	v_mfma_f32_16x16x32_bf16 v[46:49], v[110:113], v[174:177], v[46:49]
	v_mfma_f32_16x16x32_bf16 v[42:45], v[126:129], v[174:177], v[42:45]
	v_mfma_f32_16x16x32_bf16 v[30:33], v[110:113], v[182:185], v[30:33]
	v_mfma_f32_16x16x32_bf16 v[26:29], v[126:129], v[182:185], v[26:29]
	v_mfma_f32_16x16x32_bf16 v[14:17], v[110:113], v[204:207], v[14:17]
	v_mfma_f32_16x16x32_bf16 v[10:13], v[126:129], v[204:207], v[10:13]
	v_mfma_f32_16x16x32_bf16 v[54:57], v[138:141], v[162:165], v[54:57]
	v_mfma_f32_16x16x32_bf16 v[50:53], v[146:149], v[162:165], v[50:53]
	v_mfma_f32_16x16x32_bf16 v[38:41], v[138:141], v[170:173], v[38:41]
	v_mfma_f32_16x16x32_bf16 v[34:37], v[146:149], v[170:173], v[34:37]
	v_mfma_f32_16x16x32_bf16 v[22:25], v[138:141], v[178:181], v[22:25]
	v_mfma_f32_16x16x32_bf16 v[18:21], v[146:149], v[178:181], v[18:21]
	v_mfma_f32_16x16x32_bf16 v[6:9], v[138:141], v[186:189], v[6:9]
	v_mfma_f32_16x16x32_bf16 v[2:5], v[146:149], v[186:189], v[2:5]
	v_mfma_f32_16x16x32_bf16 v[54:57], v[142:145], v[166:169], v[54:57]
	v_mfma_f32_16x16x32_bf16 v[50:53], v[150:153], v[166:169], v[50:53]
	v_mfma_f32_16x16x32_bf16 v[38:41], v[142:145], v[174:177], v[38:41]
	v_mfma_f32_16x16x32_bf16 v[34:37], v[150:153], v[174:177], v[34:37]
	v_mfma_f32_16x16x32_bf16 v[22:25], v[142:145], v[182:185], v[22:25]
	v_mfma_f32_16x16x32_bf16 v[18:21], v[150:153], v[182:185], v[18:21]
	v_mfma_f32_16x16x32_bf16 v[6:9], v[142:145], v[204:207], v[6:9]
	v_mfma_f32_16x16x32_bf16 v[2:5], v[150:153], v[204:207], v[2:5]
	s_barrier
	s_add_i32 s6, 0, 0x18000
	s_add_i32 s69, 0, 0x1c000
	v_add_u32_e32 v126, s6, v230
	v_add_u32_e32 v150, s69, v230
	ds_read_b128 v[106:109], v126
	ds_read_b128 v[110:113], v126 offset:1024
	ds_read_b128 v[122:125], v126 offset:2048
	ds_read_b128 v[126:129], v126 offset:3072
	ds_read_b128 v[138:141], v150
	ds_read_b128 v[142:145], v150 offset:1024
	ds_read_b128 v[146:149], v150 offset:2048
	ds_read_b128 v[150:153], v150 offset:3072
	s_add_u32 s44, s44, s30
	s_addc_u32 s45, s45, 0
	s_mov_b32 m0, s48
	v_lshl_add_u64 v[232:233], s[44:45], 0, v[190:191]
	ds_read_b128 v[162:165], v231 offset:32768
	ds_read_b128 v[166:169], v231 offset:33792
	ds_read_b128 v[170:173], v231 offset:34816
	ds_read_b128 v[174:177], v231 offset:35840
	ds_read_b128 v[178:181], v231 offset:36864
	ds_read_b128 v[182:185], v231 offset:37888
	ds_read_b128 v[186:189], v231 offset:38912
	ds_read_b128 v[204:207], v231 offset:39936
	global_load_lds_dwordx4 v[232:233], off
	v_lshl_add_u64 v[232:233], s[44:45], 0, v[194:195]
	s_mov_b32 m0, s49
	s_nop 0
	global_load_lds_dwordx4 v[232:233], off
	s_waitcnt vmcnt(8)
	s_waitcnt lgkmcnt(0)
	s_barrier
	s_waitcnt lgkmcnt(0)
	v_mfma_f32_16x16x32_bf16 v[158:161], v[106:109], v[162:165], v[158:161]
	v_mfma_f32_16x16x32_bf16 v[154:157], v[122:125], v[162:165], v[154:157]
	v_mfma_f32_16x16x32_bf16 v[118:121], v[106:109], v[170:173], v[118:121]
	v_mfma_f32_16x16x32_bf16 v[114:117], v[122:125], v[170:173], v[114:117]
	v_mfma_f32_16x16x32_bf16 v[94:97], v[106:109], v[178:181], v[94:97]
	v_mfma_f32_16x16x32_bf16 v[90:93], v[122:125], v[178:181], v[90:93]
	v_mfma_f32_16x16x32_bf16 v[78:81], v[106:109], v[186:189], v[78:81]
	v_mfma_f32_16x16x32_bf16 v[74:77], v[122:125], v[186:189], v[74:77]
	v_mfma_f32_16x16x32_bf16 v[158:161], v[110:113], v[166:169], v[158:161]
	v_mfma_f32_16x16x32_bf16 v[154:157], v[126:129], v[166:169], v[154:157]
	v_mfma_f32_16x16x32_bf16 v[118:121], v[110:113], v[174:177], v[118:121]
	v_mfma_f32_16x16x32_bf16 v[114:117], v[126:129], v[174:177], v[114:117]
	v_mfma_f32_16x16x32_bf16 v[94:97], v[110:113], v[182:185], v[94:97]
	v_mfma_f32_16x16x32_bf16 v[90:93], v[126:129], v[182:185], v[90:93]
	v_mfma_f32_16x16x32_bf16 v[78:81], v[110:113], v[204:207], v[78:81]
	v_mfma_f32_16x16x32_bf16 v[74:77], v[126:129], v[204:207], v[74:77]
	v_mfma_f32_16x16x32_bf16 v[134:137], v[138:141], v[162:165], v[134:137]
	v_mfma_f32_16x16x32_bf16 v[130:133], v[146:149], v[162:165], v[130:133]
	v_mfma_f32_16x16x32_bf16 v[102:105], v[138:141], v[170:173], v[102:105]
	v_mfma_f32_16x16x32_bf16 v[98:101], v[146:149], v[170:173], v[98:101]
	v_mfma_f32_16x16x32_bf16 v[86:89], v[138:141], v[178:181], v[86:89]
	v_mfma_f32_16x16x32_bf16 v[82:85], v[146:149], v[178:181], v[82:85]
	v_mfma_f32_16x16x32_bf16 v[70:73], v[138:141], v[186:189], v[70:73]
	v_mfma_f32_16x16x32_bf16 v[66:69], v[146:149], v[186:189], v[66:69]
	v_mfma_f32_16x16x32_bf16 v[134:137], v[142:145], v[166:169], v[134:137]
	v_mfma_f32_16x16x32_bf16 v[130:133], v[150:153], v[166:169], v[130:133]
	v_mfma_f32_16x16x32_bf16 v[102:105], v[142:145], v[174:177], v[102:105]
	v_mfma_f32_16x16x32_bf16 v[98:101], v[150:153], v[174:177], v[98:101]
	v_mfma_f32_16x16x32_bf16 v[86:89], v[142:145], v[182:185], v[86:89]
	v_mfma_f32_16x16x32_bf16 v[82:85], v[150:153], v[182:185], v[82:85]
	v_mfma_f32_16x16x32_bf16 v[70:73], v[142:145], v[204:207], v[70:73]
	v_mfma_f32_16x16x32_bf16 v[66:69], v[150:153], v[204:207], v[66:69]
	s_barrier
; #define PG8_STAGE(bufoff, gbase, voff) do { _Pragma("unroll") for (int _i = 0; _i < 2; ++_i) \
;         __builtin_amdgcn_global_load_lds((const unsigned*)((const char*)(gbase) + (voff)[_i]), (LAS unsigned*)(lds + (bufoff) + ldsw + _i * 8192), 16, 0, 0); } while (0)
; #define PG8_LDA(dst, b, h) do { _Pragma("unroll") for (int m = 0; m < 4; ++m) _Pragma("unroll") for (int k = 0; k < 2; ++k) dst[m][k] = *(const LAS bf16x8*)(lds + PG8_SA(b, h) + aoff + m * 2048 + k * 1024); } while (0)
; #define PG8_MMA(ai, bj, At, Bt) do { __builtin_amdgcn_s_setprio(1); _Pragma("unroll") for (int m = 0; m < 4; ++m) _Pragma("unroll") for (int n = 0; n < 2; ++n) _Pragma("unroll") for (int k = 0; k < 2; ++k) \
;         acc[ai][bj][m][n] = __builtin_amdgcn_mfma_f32_16x16x32_bf16(Bt[n][k], At[m][k], acc[ai][bj][m][n], 0, 0, 0); __builtin_amdgcn_s_setprio(0); } while (0)
; #define PG8_WAIT_V(n) asm volatile("s_waitcnt vmcnt(" #n ")" ::: "memory")
; #define PG8_WAIT_L(n) asm volatile("s_waitcnt lgkmcnt(" #n ")" ::: "memory")
; #define PG8_BAR __builtin_amdgcn_s_barrier()
; #define PG8_SCHED __builtin_amdgcn_sched_barrier(0)
; template <class Epi>
; __device__ __forceinline__ void gemm_phase(LAS unsigned char* lds, const Gemm g, const StaticOrder& S, const Epi& E, const float* SS) {
;     ...
;             PG8_LDA(At, 1, 1); PG8_STAGE(PG8_SB(1, 0), b3, voffB); PG8_STAGE(PG8_SB(1, 1), b3 + hstep, voffB); PG8_STAGE(PG8_SA(1, 0), a3, voffA);
;             PG8_WAIT_V(8); PG8_WAIT_L(0); PG8_BAR; PG8_MMA(1, 0, At, B0); PG8_MMA(1, 1, At, B1); PG8_BAR; PG8_SCHED;
;         }
;         if (wr == 0) PG8_BAR;
	s_add_i32 s6, s6, s15
	v_lshl_add_u64 v[216:217], v[216:217], 0, s[64:65]
	s_mov_b32 m0, s6
	ds_read_b128 v[162:165], v231 offset:49152
	ds_read_b128 v[166:169], v231 offset:50176
	ds_read_b128 v[170:173], v231 offset:51200
	ds_read_b128 v[174:177], v231 offset:52224
	ds_read_b128 v[178:181], v231 offset:53248
	ds_read_b128 v[182:185], v231 offset:54272
	ds_read_b128 v[186:189], v231 offset:55296
	ds_read_b128 v[204:207], v231 offset:56320
	global_load_lds_dwordx4 v[216:217], off
	v_lshl_add_u64 v[216:217], v[218:219], 0, s[64:65]
	s_add_i32 m0, s6, 0x2000
	s_add_i32 s6, s69, s15
	global_load_lds_dwordx4 v[216:217], off
	v_lshl_add_u64 v[216:217], v[220:221], 0, s[64:65]
	s_mov_b32 m0, s6
	s_nop 0
	global_load_lds_dwordx4 v[216:217], off
	v_lshl_add_u64 v[216:217], v[222:223], 0, s[64:65]
	s_add_i32 m0, s6, 0x2000
	s_nop 0
	global_load_lds_dwordx4 v[216:217], off
	v_lshl_add_u64 v[216:217], v[224:225], 0, s[64:65]
	s_mov_b32 m0, s50
	s_nop 0
	global_load_lds_dwordx4 v[216:217], off
	v_lshl_add_u64 v[216:217], v[226:227], 0, s[64:65]
	s_mov_b32 m0, s51
	s_nop 0
	global_load_lds_dwordx4 v[216:217], off
	s_waitcnt vmcnt(8)
	s_waitcnt lgkmcnt(0)
	s_barrier
	s_waitcnt lgkmcnt(0)
	v_mfma_f32_16x16x32_bf16 v[62:65], v[106:109], v[162:165], v[62:65]
	v_mfma_f32_16x16x32_bf16 v[58:61], v[122:125], v[162:165], v[58:61]
	v_mfma_f32_16x16x32_bf16 v[46:49], v[106:109], v[170:173], v[46:49]
	v_mfma_f32_16x16x32_bf16 v[42:45], v[122:125], v[170:173], v[42:45]
	v_mfma_f32_16x16x32_bf16 v[30:33], v[106:109], v[178:181], v[30:33]
	v_mfma_f32_16x16x32_bf16 v[26:29], v[122:125], v[178:181], v[26:29]
	v_mfma_f32_16x16x32_bf16 v[14:17], v[106:109], v[186:189], v[14:17]
	v_mfma_f32_16x16x32_bf16 v[10:13], v[122:125], v[186:189], v[10:13]
	v_mfma_f32_16x16x32_bf16 v[62:65], v[110:113], v[166:169], v[62:65]
	v_mfma_f32_16x16x32_bf16 v[58:61], v[126:129], v[166:169], v[58:61]
	v_mfma_f32_16x16x32_bf16 v[46:49], v[110:113], v[174:177], v[46:49]
	v_mfma_f32_16x16x32_bf16 v[42:45], v[126:129], v[174:177], v[42:45]
	v_mfma_f32_16x16x32_bf16 v[30:33], v[110:113], v[182:185], v[30:33]
	v_mfma_f32_16x16x32_bf16 v[26:29], v[126:129], v[182:185], v[26:29]
	v_mfma_f32_16x16x32_bf16 v[14:17], v[110:113], v[204:207], v[14:17]
	v_mfma_f32_16x16x32_bf16 v[10:13], v[126:129], v[204:207], v[10:13]
	v_mfma_f32_16x16x32_bf16 v[54:57], v[138:141], v[162:165], v[54:57]
	v_mfma_f32_16x16x32_bf16 v[50:53], v[146:149], v[162:165], v[50:53]
	v_mfma_f32_16x16x32_bf16 v[38:41], v[138:141], v[170:173], v[38:41]
	v_mfma_f32_16x16x32_bf16 v[34:37], v[146:149], v[170:173], v[34:37]
	v_mfma_f32_16x16x32_bf16 v[22:25], v[138:141], v[178:181], v[22:25]
	v_mfma_f32_16x16x32_bf16 v[18:21], v[146:149], v[178:181], v[18:21]
	v_mfma_f32_16x16x32_bf16 v[6:9], v[138:141], v[186:189], v[6:9]
	v_mfma_f32_16x16x32_bf16 v[2:5], v[146:149], v[186:189], v[2:5]
	v_mfma_f32_16x16x32_bf16 v[54:57], v[142:145], v[166:169], v[54:57]
	v_mfma_f32_16x16x32_bf16 v[50:53], v[150:153], v[166:169], v[50:53]
	v_mfma_f32_16x16x32_bf16 v[38:41], v[142:145], v[174:177], v[38:41]
	v_mfma_f32_16x16x32_bf16 v[34:37], v[150:153], v[174:177], v[34:37]
	v_mfma_f32_16x16x32_bf16 v[22:25], v[142:145], v[182:185], v[22:25]
	v_mfma_f32_16x16x32_bf16 v[18:21], v[150:153], v[182:185], v[18:21]
	v_mfma_f32_16x16x32_bf16 v[6:9], v[142:145], v[204:207], v[6:9]
	v_mfma_f32_16x16x32_bf16 v[2:5], v[150:153], v[204:207], v[2:5]
	s_barrier
	s_add_u32 s60, s60, 0x100
	s_addc_u32 s61, s61, 0
	s_add_u32 s42, s42, 0x100
	s_addc_u32 s43, s43, 0
	s_cmp_ge_u32 s68, s53
	s_mov_b32 s44, s68
	s_cbranch_scc0 .LBB0_640
	s_and_b64 vcc, exec, s[36:37]
	s_cbranch_vccz .LBB0_643
	s_barrier
